# combined latency edits + RMSNorm next-row prefetch
# baseline (speedup 1.0000x reference)
; __device__ __forceinline__ const float* INP(const Params& p, int i) { asm volatile("" : "+s"(i)); return p.in[i]; }
; __device__ __forceinline__ int TID() { int t = threadIdx.x; asm volatile("" : "+v"(t)); return t; }
; __device__ __forceinline__ int BID() { int t = blockIdx.x; asm volatile("" : "+s"(t)); return t; }
; __device__ __forceinline__ int NBLK() { int t = gridDim.x; asm volatile("" : "+s"(t)); return t; }
; __device__ void rmsnorm_phase(const float* __restrict__ x, const float* __restrict__ g, bf16_t* h, float* outf) {
;     const int lane = TID() & 63, gw = BID() * 8 + (TID() >> 6), nw = NBLK() * 8;
;     float4 gv[4];
; #pragma unroll
;     for (int i = 0; i < 4; ++i) gv[i] = ((const float4*)g)[lane + 64 * i];
;     for (int row = gw; row < T_; row += nw) {
;         const float4* xr = (const float4*)(x + (size_t)row * D_);
;         float4 v[4]; float ss = 0.f;
; #pragma unroll
;         for (int i = 0; i < 4; ++i) { v[i] = xr[lane + 64 * i]; ss += v[i].x * v[i].x + v[i].y * v[i].y + v[i].z * v[i].z + v[i].w * v[i].w; }
; #pragma unroll
;         for (int o = 32; o >= 1; o >>= 1) ss += __shfl_xor(ss, o);
; __global__ void __launch_bounds__(512, 2) fwd_kernel(Params p, int ph_lo, int ph_hi) {
;     ...
;             case 11: if (PHON(11)) rmsnorm_phase(xo, INP(p, 31) + (size_t)l * D_, H, nullptr); break;
.LBB0_77:
	s_andn2_b64 vcc, exec, s[2:3]
	s_cbranch_vccnz .LBB0_113
	v_readlane_b32 s2, v254, 37
	s_cmp_gt_i32 s2, 10
	s_mov_b64 s[2:3], -1
	s_cbranch_scc0 .LBB0_83
	s_mov_b32 s4, 31
	v_mov_b32_e32 v0, v168
	s_mov_b32 s2, s73
	v_mov_b32_e32 v2, v168
	s_mov_b32 s6, s39
	v_ashrrev_i32_e32 v2, 6, v2
	s_waitcnt vmcnt(0)
	v_lshl_add_u32 v18, s2, 3, v2
	v_cmp_gt_i32_e32 vcc, s58, v18
	s_and_saveexec_b64 s[2:3], vcc
	s_cbranch_execz .LBB0_82
	s_ashr_i32 s5, s4, 31
	s_lshl_b64 s[4:5], s[4:5], 3
	s_add_u32 s4, s0, s4
	s_addc_u32 s5, s1, s5
	s_load_dwordx2 s[4:5], s[4:5], 0x0
	v_readlane_b32 s8, v254, 31
	v_readlane_b32 s9, v254, 32
	s_mov_b32 s10, s8
	s_ashr_i32 s11, s8, 31
	v_writelane_b32 v254, s8, 31
	v_and_b32_e32 v22, 63, v0
	v_lshlrev_b32_e32 v29, 4, v22
	v_writelane_b32 v254, s9, 32
	s_lshl_b64 s[8:9], s[10:11], 12
	s_waitcnt lgkmcnt(0)
	s_add_u32 s4, s4, s8
	s_addc_u32 s5, s5, s9
	global_load_dwordx4 v[2:5], v29, s[4:5]
	global_load_dwordx4 v[6:9], v29, s[4:5] offset:1024
	global_load_dwordx4 v[10:13], v29, s[4:5] offset:2048
	global_load_dwordx4 v[14:17], v29, s[4:5] offset:3072
	v_and_b32_e32 v0, 64, v174
	v_add_u32_e32 v19, 64, v0
	v_xor_b32_e32 v0, 32, v174
	v_cmp_lt_i32_e32 vcc, v0, v19
	v_xor_b32_e32 v20, 16, v174
	s_lshl_b32 s4, s6, 3
	v_cndmask_b32_e32 v0, v174, v0, vcc
	v_cmp_lt_i32_e32 vcc, v20, v19
	v_readlane_b32 s6, v254, 33
	v_readlane_b32 s7, v254, 34
	v_cndmask_b32_e32 v20, v174, v20, vcc
	v_lshlrev_b32_e32 v24, 2, v20
	v_xor_b32_e32 v20, 8, v174
	v_cmp_lt_i32_e32 vcc, v20, v19
	s_ashr_i32 s5, s4, 31
	v_lshlrev_b32_e32 v0, 2, v0
	v_cndmask_b32_e32 v20, v174, v20, vcc
	v_lshlrev_b32_e32 v25, 2, v20
	v_xor_b32_e32 v20, 4, v174
	v_cmp_lt_i32_e32 vcc, v20, v19
	s_lshl_b64 s[8:9], s[4:5], 12
	s_mov_b64 s[10:11], 0
	v_cndmask_b32_e32 v20, v174, v20, vcc
	v_lshlrev_b32_e32 v26, 2, v20
	v_xor_b32_e32 v20, 2, v174
	v_cmp_lt_i32_e32 vcc, v20, v19
	s_nop 1
	v_cndmask_b32_e32 v20, v174, v20, vcc
	v_lshlrev_b32_e32 v27, 2, v20
	v_xor_b32_e32 v20, 1, v174
	v_cmp_lt_i32_e32 vcc, v20, v19
	s_nop 1
	v_cndmask_b32_e32 v19, v174, v20, vcc
	v_lshlrev_b32_e32 v28, 2, v19
	v_ashrrev_i32_e32 v19, 31, v18
	v_lshlrev_b64 v[20:21], 11, v[18:19]
	v_lshl_or_b32 v20, v22, 3, v20
	v_lshlrev_b64 v[22:23], 12, v[18:19]
	v_or_b32_e32 v22, v22, v29
	v_lshl_add_u64 v[20:21], s[6:7], 0, v[20:21]
	s_lshl_b64 s[6:7], s[4:5], 11
	v_lshl_add_u64 v[22:23], s[78:79], 0, v[22:23]
	v_readfirstlane_b32 s5, v18
	global_load_dwordx4 v[30:33], v[22:23], off nt
	global_load_dwordx4 v[34:37], v[22:23], off offset:1024 nt
	global_load_dwordx4 v[56:59], v[22:23], off offset:2048 nt
	global_load_dwordx4 v[60:63], v[22:23], off offset:3072 nt
	v_lshl_add_u64 v[22:23], v[22:23], 0, s[8:9]
.LBB0_81:
	v_add_u32_e32 v18, s4, v18
	s_add_i32 s5, s5, s4
	s_cmp_lt_i32 s5, s58
	s_cbranch_scc0 .Lrn81_nopf
	global_load_dwordx4 v[64:67], v[22:23], off nt
	global_load_dwordx4 v[68:71], v[22:23], off offset:1024 nt
	global_load_dwordx4 v[72:75], v[22:23], off offset:2048 nt
	global_load_dwordx4 v[76:79], v[22:23], off offset:3072 nt
	v_lshl_add_u64 v[22:23], v[22:23], 0, s[8:9]
	s_waitcnt vmcnt(4)
	s_branch .Lrn81_go

; __device__ __forceinline__ int TID() { int t = threadIdx.x; asm volatile("" : "+v"(t)); return t; }
; __device__ __forceinline__ int BID() { int t = blockIdx.x; asm volatile("" : "+s"(t)); return t; }
; __device__ __forceinline__ int NBLK() { int t = gridDim.x; asm volatile("" : "+s"(t)); return t; }
; __device__ void rmsnorm_phase(const float* __restrict__ x, const float* __restrict__ g, bf16_t* h, float* outf) {
;     const int lane = TID() & 63, gw = BID() * 8 + (TID() >> 6), nw = NBLK() * 8;
;     float4 gv[4];
; #pragma unroll
;     for (int i = 0; i < 4; ++i) gv[i] = ((const float4*)g)[lane + 64 * i];
;     for (int row = gw; row < T_; row += nw) {
;         const float4* xr = (const float4*)(x + (size_t)row * D_);
;         float4 v[4]; float ss = 0.f;
; #pragma unroll
;         for (int i = 0; i < 4; ++i) { v[i] = xr[lane + 64 * i]; ss += v[i].x * v[i].x + v[i].y * v[i].y + v[i].z * v[i].z + v[i].w * v[i].w; }
.LBB0_223:
	s_mov_b32 s4, 5
	v_mov_b32_e32 v0, v168
	s_mov_b32 s2, s73
	v_mov_b32_e32 v2, v168
	s_mov_b32 s6, s39
	v_ashrrev_i32_e32 v2, 6, v2
	v_lshl_add_u32 v18, s2, 3, v2
	v_cmp_gt_i32_e32 vcc, s58, v18
	s_and_saveexec_b64 s[2:3], vcc
	s_cbranch_execz .LBB0_226
	s_ashr_i32 s5, s4, 31
	s_lshl_b64 s[4:5], s[4:5], 3
	s_add_u32 s4, s0, s4
	s_addc_u32 s5, s1, s5
	s_load_dwordx2 s[4:5], s[4:5], 0x0
	v_readlane_b32 s8, v254, 31
	v_readlane_b32 s9, v254, 32
	s_lshl_b64 s[8:9], s[8:9], 12
	v_and_b32_e32 v22, 63, v0
	s_waitcnt lgkmcnt(0)
	s_add_u32 s4, s4, s8
	v_lshlrev_b32_e32 v29, 4, v22
	s_addc_u32 s5, s5, s9
	global_load_dwordx4 v[2:5], v29, s[4:5]
	global_load_dwordx4 v[6:9], v29, s[4:5] offset:1024
	global_load_dwordx4 v[10:13], v29, s[4:5] offset:2048
	global_load_dwordx4 v[14:17], v29, s[4:5] offset:3072
	v_and_b32_e32 v0, 64, v174
	v_add_u32_e32 v19, 64, v0
	v_xor_b32_e32 v0, 32, v174
	v_cmp_lt_i32_e32 vcc, v0, v19
	v_xor_b32_e32 v20, 16, v174
	s_lshl_b32 s4, s6, 3
	v_cndmask_b32_e32 v0, v174, v0, vcc
	v_cmp_lt_i32_e32 vcc, v20, v19
	v_readlane_b32 s6, v254, 33
	v_readlane_b32 s7, v254, 34
	v_cndmask_b32_e32 v20, v174, v20, vcc
	v_lshlrev_b32_e32 v24, 2, v20
	v_xor_b32_e32 v20, 8, v174
	v_cmp_lt_i32_e32 vcc, v20, v19
	s_ashr_i32 s5, s4, 31
	v_lshlrev_b32_e32 v0, 2, v0
	v_cndmask_b32_e32 v20, v174, v20, vcc
	v_lshlrev_b32_e32 v25, 2, v20
	v_xor_b32_e32 v20, 4, v174
	v_cmp_lt_i32_e32 vcc, v20, v19
	s_lshl_b64 s[8:9], s[4:5], 12
	s_mov_b64 s[10:11], 0
	v_cndmask_b32_e32 v20, v174, v20, vcc
	v_lshlrev_b32_e32 v26, 2, v20
	v_xor_b32_e32 v20, 2, v174
	v_cmp_lt_i32_e32 vcc, v20, v19
	s_nop 1
	v_cndmask_b32_e32 v20, v174, v20, vcc
	v_lshlrev_b32_e32 v27, 2, v20
	v_xor_b32_e32 v20, 1, v174
	v_cmp_lt_i32_e32 vcc, v20, v19
	s_nop 1
	v_cndmask_b32_e32 v19, v174, v20, vcc
	v_lshlrev_b32_e32 v28, 2, v19
	v_ashrrev_i32_e32 v19, 31, v18
	v_lshlrev_b64 v[20:21], 11, v[18:19]
	v_lshl_or_b32 v20, v22, 3, v20
	v_lshlrev_b64 v[22:23], 12, v[18:19]
	v_or_b32_e32 v22, v22, v29
	v_lshl_add_u64 v[20:21], s[6:7], 0, v[20:21]
	s_lshl_b64 s[6:7], s[4:5], 11
	v_lshl_add_u64 v[22:23], s[78:79], 0, v[22:23]
	v_readfirstlane_b32 s5, v18
	global_load_dwordx4 v[30:33], v[22:23], off nt
	global_load_dwordx4 v[34:37], v[22:23], off offset:1024 nt
	global_load_dwordx4 v[56:59], v[22:23], off offset:2048 nt
	global_load_dwordx4 v[60:63], v[22:23], off offset:3072 nt
	v_lshl_add_u64 v[22:23], v[22:23], 0, s[8:9]

; __device__ __forceinline__ int TID() { int t = threadIdx.x; asm volatile("" : "+v"(t)); return t; }
; __device__ __forceinline__ int BID() { int t = blockIdx.x; asm volatile("" : "+s"(t)); return t; }
; __device__ __forceinline__ int NBLK() { int t = gridDim.x; asm volatile("" : "+s"(t)); return t; }
; __device__ void rmsnorm_phase(const float* __restrict__ x, const float* __restrict__ g, bf16_t* h, float* outf) {
;     const int lane = TID() & 63, gw = BID() * 8 + (TID() >> 6), nw = NBLK() * 8;
;     float4 gv[4];
; #pragma unroll
;     for (int i = 0; i < 4; ++i) gv[i] = ((const float4*)g)[lane + 64 * i];
;     for (int row = gw; row < T_; row += nw) {
;         const float4* xr = (const float4*)(x + (size_t)row * D_);
;         float4 v[4]; float ss = 0.f;
; #pragma unroll
;         for (int i = 0; i < 4; ++i) { v[i] = xr[lane + 64 * i]; ss += v[i].x * v[i].x + v[i].y * v[i].y + v[i].z * v[i].z + v[i].w * v[i].w; }
.LBB0_599:
	s_and_b64 vcc, exec, s[2:3]
	s_cbranch_vccz .LBB0_604
	s_mov_b32 s4, 5
	v_mov_b32_e32 v0, v168
	s_mov_b32 s2, s73
	v_mov_b32_e32 v2, v168
	s_mov_b32 s6, s39
	v_ashrrev_i32_e32 v2, 6, v2
	s_waitcnt vmcnt(0)
	v_lshl_add_u32 v18, s2, 3, v2
	v_cmp_gt_i32_e32 vcc, s58, v18
	s_and_saveexec_b64 s[2:3], vcc
	s_cbranch_execz .LBB0_603
	s_ashr_i32 s5, s4, 31
	s_lshl_b64 s[4:5], s[4:5], 3
	s_add_u32 s4, s0, s4
	s_addc_u32 s5, s1, s5
	s_load_dwordx2 s[4:5], s[4:5], 0x0
	v_readlane_b32 s8, v254, 31
	v_readlane_b32 s9, v254, 32
	s_mov_b32 s10, s8
	s_ashr_i32 s11, s8, 31
	v_writelane_b32 v254, s8, 31
	v_and_b32_e32 v22, 63, v0
	v_lshlrev_b32_e32 v29, 4, v22
	v_writelane_b32 v254, s9, 32
	s_lshl_b64 s[8:9], s[10:11], 12
	s_waitcnt lgkmcnt(0)
	s_add_u32 s4, s4, s8
	s_addc_u32 s5, s5, s9
	global_load_dwordx4 v[2:5], v29, s[4:5]
	global_load_dwordx4 v[6:9], v29, s[4:5] offset:1024
	global_load_dwordx4 v[10:13], v29, s[4:5] offset:2048
	global_load_dwordx4 v[14:17], v29, s[4:5] offset:3072
	v_and_b32_e32 v0, 64, v174
	v_add_u32_e32 v19, 64, v0
	v_xor_b32_e32 v0, 32, v174
	v_cmp_lt_i32_e32 vcc, v0, v19
	v_xor_b32_e32 v20, 16, v174
	s_lshl_b32 s4, s6, 3
	v_cndmask_b32_e32 v0, v174, v0, vcc
	v_cmp_lt_i32_e32 vcc, v20, v19
	v_readlane_b32 s6, v254, 33
	v_readlane_b32 s7, v254, 34
	v_cndmask_b32_e32 v20, v174, v20, vcc
	v_lshlrev_b32_e32 v24, 2, v20
	v_xor_b32_e32 v20, 8, v174
	v_cmp_lt_i32_e32 vcc, v20, v19
	s_ashr_i32 s5, s4, 31
	v_lshlrev_b32_e32 v0, 2, v0
	v_cndmask_b32_e32 v20, v174, v20, vcc
	v_lshlrev_b32_e32 v25, 2, v20
	v_xor_b32_e32 v20, 4, v174
	v_cmp_lt_i32_e32 vcc, v20, v19
	s_lshl_b64 s[8:9], s[4:5], 12
	s_mov_b64 s[10:11], 0
	v_cndmask_b32_e32 v20, v174, v20, vcc
	v_lshlrev_b32_e32 v26, 2, v20
	v_xor_b32_e32 v20, 2, v174
	v_cmp_lt_i32_e32 vcc, v20, v19
	s_nop 1
	v_cndmask_b32_e32 v20, v174, v20, vcc
	v_lshlrev_b32_e32 v27, 2, v20
	v_xor_b32_e32 v20, 1, v174
	v_cmp_lt_i32_e32 vcc, v20, v19
	s_nop 1
	v_cndmask_b32_e32 v19, v174, v20, vcc
	v_lshlrev_b32_e32 v28, 2, v19
	v_ashrrev_i32_e32 v19, 31, v18
	v_lshlrev_b64 v[20:21], 11, v[18:19]
	v_lshl_or_b32 v20, v22, 3, v20
	v_lshlrev_b64 v[22:23], 12, v[18:19]
	v_or_b32_e32 v22, v22, v29
	v_lshl_add_u64 v[20:21], s[6:7], 0, v[20:21]
	s_lshl_b64 s[6:7], s[4:5], 11
	v_lshl_add_u64 v[22:23], s[78:79], 0, v[22:23]
	v_readfirstlane_b32 s5, v18
	global_load_dwordx4 v[30:33], v[22:23], off nt
	global_load_dwordx4 v[34:37], v[22:23], off offset:1024 nt
	global_load_dwordx4 v[56:59], v[22:23], off offset:2048 nt
	global_load_dwordx4 v[60:63], v[22:23], off offset:3072 nt
	v_lshl_add_u64 v[22:23], v[22:23], 0, s[8:9]
